# PROJ: pad N-tile (32 valid cols) moved to last half-round and computed with 1/4 of the MFMA/B-load work
# speedup vs baseline: 1.1109x; 1.0126x over previous
.LBB0_449:
	s_cmpk_lt_u32 s43, 0x180
	s_cbranch_scc0 .Lproj_ci
	s_mul_i32 s4, s43, 0x2ab
	s_lshr_b32 s4, s4, 16
	s_mul_i32 s5, s4, 0x60
	s_lshl_b32 s6, s4, 6
	s_lshl_b32 s4, s43, 3
	s_and_b32 s4, s4, 56
	s_or_b32 s16, s4, s6
	s_sub_i32 s5, s43, s5
	s_lshl_b32 s5, s5, 5
	s_and_b32 s17, s5, 0xf00
	s_branch .Lproj_cd
.Lproj_ci:
	s_sub_u32 s16, s43, 0x180
	s_lshl_b32 s16, s16, 3
	s_movk_i32 s17, 0xc00
	s_mov_b32 s6, s16
.Lproj_cd:
	s_or_b32 s4, s16, s67
	v_mov_b32 v10, v198
	v_ashrrev_i32_e32 v0, 2, v10
	s_lshl_b32 s4, s4, 7
	v_add_u32_e32 v2, s4, v0
	v_ashrrev_i32_e32 v3, 31, v2
	v_lshlrev_b64 v[2:3], 11, v[2:3]
	v_lshlrev_b32_e32 v1, 4, v10
	v_add_u32_e32 v4, s17, v0
	v_lshl_add_u64 v[2:3], s[96:97], 0, v[2:3]
	v_and_b32_e32 v152, 48, v1
	v_ashrrev_i32_e32 v5, 31, v4
	v_lshl_add_u64 v[2:3], v[2:3], 0, v[152:153]
	v_lshlrev_b64 v[4:5], 11, v[4:5]
	v_lshl_add_u64 v[156:157], s[8:9], 0, v[4:5]
	v_add_co_u32_e32 v6, vcc, s62, v2
	v_lshl_add_u64 v[4:5], v[156:157], 0, v[152:153]
	s_nop 0
	v_addc_co_u32_e32 v7, vcc, 0, v3, vcc
	v_add_co_u32_e32 v8, vcc, s62, v4
	s_and_b32 s7, s42, 56
	v_lshrrev_b32_e32 v1, 2, v10
	s_or_b32 s6, s67, s6
	v_addc_co_u32_e32 v9, vcc, 0, v5, vcc
	v_and_b32_e32 v12, 12, v1
	s_movk_i32 s20, 0x1230
	s_or_b32 s84, s6, s7
	v_add_co_u32_e32 v60, vcc, s33, v4
	v_lshrrev_b32_e64 v12, v12, s20
	s_lshl_b64 s[6:7], s[84:85], 18
	v_addc_co_u32_e32 v61, vcc, 0, v5, vcc
	v_and_b32_e32 v11, 3, v10
	v_ashrrev_i32_e32 v1, 31, v0
	v_xor_b32_e32 v10, v12, v10
	s_add_u32 s6, s82, s6
	v_add_co_u32_e32 v62, vcc, s72, v4
	v_lshlrev_b32_e32 v13, 6, v0
	v_lshlrev_b64 v[0:1], 11, v[0:1]
	v_lshlrev_b32_e32 v10, 4, v10
	s_addc_u32 s7, s83, s7
	v_addc_co_u32_e32 v63, vcc, 0, v5, vcc
	s_nop 0
	v_readfirstlane_b32 s26, v2
	v_readfirstlane_b32 s27, v3
	v_readfirstlane_b32 s28, v4
	v_readfirstlane_b32 s29, v5
	v_lshrrev_b32_e32 v250, 6, v198
	s_nop 0
	v_readfirstlane_b32 s24, v250
	s_lshl_b32 s24, s24, 10
	v_lshrrev_b32_e32 v250, 2, v200
	v_lshrrev_b32_e32 v251, 4, v200
	v_lshlrev_b32_e32 v251, 2, v251
	v_mov_b32_e32 v248, 0x1230
	v_lshrrev_b32_e32 v251, v251, v248
	v_xor_b32_e32 v251, v251, v200
	v_and_b32_e32 v251, 3, v251
	v_lshlrev_b32_e32 v251, 4, v251
	v_lshl_add_u32 v244, v250, 11, v251
	v_add_u32_e32 v245, 0x20000, v244
	v_add_u32_e32 v246, 0x40000, v244
	v_add_u32_e32 v247, 0x60000, v244
	s_mov_b32 s25, 0
	s_add_u32 m0, s25, s24
	s_nop 0
	global_load_lds_dwordx4 v244, s[26:27]
	s_add_u32 m0, m0, 0x1000
	s_nop 0
	global_load_lds_dwordx4 v245, s[26:27]
	s_add_u32 m0, m0, 0x1000
	s_nop 0
	global_load_lds_dwordx4 v244, s[28:29]
	s_add_u32 m0, m0, 0x1000
	s_nop 0
	global_load_lds_dwordx4 v245, s[28:29]
	s_add_u32 m0, m0, 0x1000
	s_nop 0
	global_load_lds_dwordx4 v246, s[28:29]
	s_add_u32 m0, m0, 0x1000
	s_nop 0
	global_load_lds_dwordx4 v247, s[28:29]
	s_add_u32 s26, s26, 64
	s_addc_u32 s27, s27, 0
	s_add_u32 s28, s28, 64
	s_addc_u32 s29, s29, 0
	s_add_u32 s25, s25, 24576
	s_cmp_eq_u32 s25, 73728
	s_cselect_b32 s25, 0, s25
	s_add_u32 m0, s25, s24
	s_nop 0
	global_load_lds_dwordx4 v244, s[26:27]
	s_add_u32 m0, m0, 0x1000
	s_nop 0
	global_load_lds_dwordx4 v245, s[26:27]
	s_add_u32 m0, m0, 0x1000
	s_nop 0
	global_load_lds_dwordx4 v244, s[28:29]
	s_add_u32 m0, m0, 0x1000
	s_nop 0
	global_load_lds_dwordx4 v245, s[28:29]
	s_add_u32 m0, m0, 0x1000
	s_nop 0
	global_load_lds_dwordx4 v246, s[28:29]
	s_add_u32 m0, m0, 0x1000
	s_nop 0
	global_load_lds_dwordx4 v247, s[28:29]
	s_add_u32 s26, s26, 64
	s_addc_u32 s27, s27, 0
	s_add_u32 s28, s28, 64
	s_addc_u32 s29, s29, 0
	s_add_u32 s25, s25, 24576
	s_cmp_eq_u32 s25, 73728
	s_cselect_b32 s25, 0, s25
	s_add_u32 m0, s25, s24
	s_nop 0
	global_load_lds_dwordx4 v244, s[26:27]
	s_add_u32 m0, m0, 0x1000
	s_nop 0
	global_load_lds_dwordx4 v245, s[26:27]
	s_add_u32 m0, m0, 0x1000
	s_nop 0
	global_load_lds_dwordx4 v244, s[28:29]
	s_add_u32 m0, m0, 0x1000
	s_nop 0
	global_load_lds_dwordx4 v245, s[28:29]
	s_add_u32 m0, m0, 0x1000
	s_nop 0
	global_load_lds_dwordx4 v246, s[28:29]
	s_add_u32 m0, m0, 0x1000
	s_nop 0
	global_load_lds_dwordx4 v247, s[28:29]
	s_add_u32 s26, s26, 64
	s_addc_u32 s27, s27, 0
	s_add_u32 s28, s28, 64
	s_addc_u32 s29, s29, 0
	s_add_u32 s25, s25, 24576
	s_cmp_eq_u32 s25, 73728
	s_cselect_b32 s25, 0, s25
	v_mov_b32_e32 v24, 0
	v_mov_b32_e32 v25, v24
	v_mov_b32_e32 v26, v24
	v_mov_b32_e32 v27, v24
	v_mov_b32_e32 v28, v24
	v_mov_b32_e32 v29, v24
	v_mov_b32_e32 v30, v24
	v_mov_b32_e32 v31, v24
	v_mov_b32_e32 v32, v24
	v_mov_b32_e32 v33, v24
	v_mov_b32_e32 v34, v24
	v_mov_b32_e32 v35, v24
	v_mov_b32_e32 v64, v24
	v_mov_b32_e32 v65, v24
	v_mov_b32_e32 v66, v24
	v_mov_b32_e32 v67, v24
	v_mov_b32_e32 v68, v24
	v_mov_b32_e32 v69, v24
	v_mov_b32_e32 v70, v24
	v_mov_b32_e32 v71, v24
	v_mov_b32_e32 v60, v24
	v_mov_b32_e32 v61, v24
	v_mov_b32_e32 v62, v24
	v_mov_b32_e32 v63, v24
	v_mov_b32_e32 v100, v24
	v_mov_b32_e32 v101, v24
	v_mov_b32_e32 v102, v24
	v_mov_b32_e32 v103, v24
	v_mov_b32_e32 v104, v24
	v_mov_b32_e32 v105, v24
	v_mov_b32_e32 v106, v24
	v_mov_b32_e32 v107, v24
	v_mov_b32_e32 v120, v24
	v_mov_b32_e32 v121, v24
	v_mov_b32_e32 v122, v24
	v_mov_b32_e32 v36, v24
	v_mov_b32_e32 v37, v24
	v_mov_b32_e32 v38, v24
	v_mov_b32_e32 v39, v24
	v_mov_b32_e32 v52, v24
	v_mov_b32_e32 v53, v24
	v_mov_b32_e32 v54, v24
	v_mov_b32_e32 v55, v24
	v_mov_b32_e32 v56, v24
	v_mov_b32_e32 v57, v24
	v_mov_b32_e32 v58, v24
	v_mov_b32_e32 v59, v24
	v_mov_b32_e32 v40, v24
	v_mov_b32_e32 v41, v24
	v_mov_b32_e32 v42, v24
	v_mov_b32_e32 v43, v24
	v_mov_b32_e32 v44, v24
	v_mov_b32_e32 v45, v24
	v_mov_b32_e32 v46, v24
	v_mov_b32_e32 v47, v24
	v_mov_b32_e32 v48, v24
	v_mov_b32_e32 v49, v24
	v_mov_b32_e32 v50, v24
	v_mov_b32_e32 v51, v24
	v_mov_b32_e32 v123, v24
	v_mov_b32_e32 v128, v24
	v_mov_b32_e32 v129, v24
	v_mov_b32_e32 v130, v24
	v_mov_b32_e32 v131, v24
	v_mov_b32_e32 v108, v24
	v_mov_b32_e32 v109, v24
	v_mov_b32_e32 v110, v24
	v_mov_b32_e32 v111, v24
	v_mov_b32_e32 v112, v24
	v_mov_b32_e32 v113, v24
	v_mov_b32_e32 v114, v24
	v_mov_b32_e32 v115, v24
	v_mov_b32_e32 v116, v24
	v_mov_b32_e32 v117, v24
	v_mov_b32_e32 v118, v24
	v_mov_b32_e32 v119, v24
	v_mov_b32_e32 v124, v24
	v_mov_b32_e32 v125, v24
	v_mov_b32_e32 v126, v24
	v_mov_b32_e32 v127, v24
	v_mov_b32_e32 v80, v24
	v_mov_b32_e32 v81, v24
	v_mov_b32_e32 v82, v24
	v_mov_b32_e32 v83, v24
	v_mov_b32_e32 v88, v24
	v_mov_b32_e32 v89, v24
	v_mov_b32_e32 v90, v24
	v_mov_b32_e32 v91, v24
	v_mov_b32_e32 v92, v24
	v_mov_b32_e32 v93, v24
	v_mov_b32_e32 v94, v24
	v_mov_b32_e32 v95, v24
	v_mov_b32_e32 v76, v24
	v_mov_b32_e32 v77, v24
	v_mov_b32_e32 v78, v24
	v_mov_b32_e32 v79, v24
	v_mov_b32_e32 v132, v24
	v_mov_b32_e32 v133, v24
	v_mov_b32_e32 v134, v24
	v_mov_b32_e32 v135, v24
	v_mov_b32_e32 v136, v24
	v_mov_b32_e32 v137, v24
	v_mov_b32_e32 v138, v24
	v_mov_b32_e32 v139, v24
	v_mov_b32_e32 v140, v24
	v_mov_b32_e32 v141, v24
	v_mov_b32_e32 v142, v24
	v_mov_b32_e32 v143, v24
	v_mov_b32_e32 v144, v24
	v_mov_b32_e32 v145, v24
	v_mov_b32_e32 v146, v24
	v_mov_b32_e32 v147, v24
	v_mov_b32_e32 v96, v24
	v_mov_b32_e32 v97, v24
	v_mov_b32_e32 v98, v24
	v_mov_b32_e32 v99, v24
	v_mov_b32_e32 v84, v24
	v_mov_b32_e32 v85, v24
	v_mov_b32_e32 v86, v24
	v_mov_b32_e32 v87, v24
	v_mov_b32_e32 v72, v24
	v_mov_b32_e32 v73, v24
	v_mov_b32_e32 v74, v24
	v_mov_b32_e32 v75, v24
	v_mov_b32_e32 v148, v24
	v_mov_b32_e32 v149, v24
	v_mov_b32_e32 v150, v24
	v_mov_b32_e32 v151, v24
	s_waitcnt vmcnt(12)
	s_barrier
	s_mov_b32 s30, 0
	v_add_u32_e32 v248, s30, v155
	v_add_u32_e32 v249, s30, v160
	ds_read_b128 v[186:189], v248
	ds_read_b128 v[212:215], v249 offset:8192
	ds_read_b128 v[190:193], v248 offset:1024
	ds_read_b128 v[216:219], v249 offset:9216
	ds_read_b128 v[194:197], v248 offset:2048
	ds_read_b128 v[220:223], v249 offset:10240
	ds_read_b128 v[208:211], v248 offset:3072
	ds_read_b128 v[224:227], v249 offset:11264
	ds_read_b128 v[228:231], v249 offset:12288
	ds_read_b128 v[232:235], v249 offset:13312
	ds_read_b128 v[236:239], v249 offset:14336
	ds_read_b128 v[240:243], v249 offset:15360
	s_add_u32 s30, s30, 24576
	s_cmp_eq_u32 s30, 73728
	s_cselect_b32 s30, 0, s30
	s_waitcnt vmcnt(6)
	s_waitcnt lgkmcnt(0)
	s_barrier
	s_mov_b32 s31, 14
	s_cmpk_lt_u32 s43, 0x180
	s_cbranch_scc0 .Lgm3_cheap
.Lgm3_loop:
	v_add_u32_e32 v248, s30, v155
	v_add_u32_e32 v249, s30, v160
	v_mfma_f32_16x16x32_bf16 v[128:131], v[212:215], v[186:189], v[128:131]
	ds_read_b128 v[0:3], v248
	v_mfma_f32_16x16x32_bf16 v[68:71], v[212:215], v[190:193], v[68:71]
	ds_read_b128 v[16:19], v249 offset:8192
	v_mfma_f32_16x16x32_bf16 v[108:111], v[212:215], v[194:197], v[108:111]
	ds_read_b128 v[4:7], v248 offset:1024
	v_mfma_f32_16x16x32_bf16 v[132:135], v[212:215], v[208:211], v[132:135]
	ds_read_b128 v[20:23], v249 offset:9216
	v_mfma_f32_16x16x32_bf16 v[120:123], v[216:219], v[186:189], v[120:123]
	ds_read_b128 v[8:11], v248 offset:2048
	v_mfma_f32_16x16x32_bf16 v[64:67], v[216:219], v[190:193], v[64:67]
	ds_read_b128 v[162:165], v249 offset:10240
	v_mfma_f32_16x16x32_bf16 v[112:115], v[216:219], v[194:197], v[112:115]
	ds_read_b128 v[12:15], v248 offset:3072
	v_mfma_f32_16x16x32_bf16 v[136:139], v[216:219], v[208:211], v[136:139]
	ds_read_b128 v[166:169], v249 offset:11264
	v_mfma_f32_16x16x32_bf16 v[104:107], v[220:223], v[186:189], v[104:107]
	ds_read_b128 v[170:173], v249 offset:12288
	v_mfma_f32_16x16x32_bf16 v[56:59], v[220:223], v[190:193], v[56:59]
	ds_read_b128 v[174:177], v249 offset:13312
	v_mfma_f32_16x16x32_bf16 v[116:119], v[220:223], v[194:197], v[116:119]
	ds_read_b128 v[178:181], v249 offset:14336
	v_mfma_f32_16x16x32_bf16 v[140:143], v[220:223], v[208:211], v[140:143]
	ds_read_b128 v[182:185], v249 offset:15360
	s_add_u32 m0, s25, s24
	v_mfma_f32_16x16x32_bf16 v[100:103], v[224:227], v[186:189], v[100:103]
	global_load_lds_dwordx4 v244, s[26:27]
	v_mfma_f32_16x16x32_bf16 v[52:55], v[224:227], v[190:193], v[52:55]
	v_mfma_f32_16x16x32_bf16 v[124:127], v[224:227], v[194:197], v[124:127]
	s_add_u32 m0, m0, 0x1000
	v_mfma_f32_16x16x32_bf16 v[144:147], v[224:227], v[208:211], v[144:147]
	global_load_lds_dwordx4 v245, s[26:27]
	v_mfma_f32_16x16x32_bf16 v[60:63], v[228:231], v[186:189], v[60:63]
	v_mfma_f32_16x16x32_bf16 v[36:39], v[228:231], v[190:193], v[36:39]
	s_add_u32 m0, m0, 0x1000
	v_mfma_f32_16x16x32_bf16 v[80:83], v[228:231], v[194:197], v[80:83]
	global_load_lds_dwordx4 v244, s[28:29]
	v_mfma_f32_16x16x32_bf16 v[96:99], v[228:231], v[208:211], v[96:99]
	v_mfma_f32_16x16x32_bf16 v[48:51], v[232:235], v[186:189], v[48:51]
	s_add_u32 m0, m0, 0x1000
	v_mfma_f32_16x16x32_bf16 v[32:35], v[232:235], v[190:193], v[32:35]
	global_load_lds_dwordx4 v245, s[28:29]
	v_mfma_f32_16x16x32_bf16 v[88:91], v[232:235], v[194:197], v[88:91]
	v_mfma_f32_16x16x32_bf16 v[84:87], v[232:235], v[208:211], v[84:87]
	s_add_u32 m0, m0, 0x1000
	v_mfma_f32_16x16x32_bf16 v[44:47], v[236:239], v[186:189], v[44:47]
	global_load_lds_dwordx4 v246, s[28:29]
	v_mfma_f32_16x16x32_bf16 v[28:31], v[236:239], v[190:193], v[28:31]
	v_mfma_f32_16x16x32_bf16 v[92:95], v[236:239], v[194:197], v[92:95]
	s_add_u32 m0, m0, 0x1000
	v_mfma_f32_16x16x32_bf16 v[72:75], v[236:239], v[208:211], v[72:75]
	global_load_lds_dwordx4 v247, s[28:29]
	v_mfma_f32_16x16x32_bf16 v[40:43], v[240:243], v[186:189], v[40:43]
	v_mfma_f32_16x16x32_bf16 v[24:27], v[240:243], v[190:193], v[24:27]
	v_mfma_f32_16x16x32_bf16 v[76:79], v[240:243], v[194:197], v[76:79]
	v_mfma_f32_16x16x32_bf16 v[148:151], v[240:243], v[208:211], v[148:151]
	s_add_u32 s26, s26, 64
	s_addc_u32 s27, s27, 0
	s_add_u32 s28, s28, 64
	s_addc_u32 s29, s29, 0
	s_add_u32 s25, s25, 24576
	s_cmp_eq_u32 s25, 73728
	s_cselect_b32 s25, 0, s25
	s_add_u32 s30, s30, 24576
	s_cmp_eq_u32 s30, 73728
	s_cselect_b32 s30, 0, s30
	s_waitcnt vmcnt(6)
	s_waitcnt lgkmcnt(0)
	s_barrier
	v_add_u32_e32 v248, s30, v155
	v_add_u32_e32 v249, s30, v160
	v_mfma_f32_16x16x32_bf16 v[128:131], v[16:19], v[0:3], v[128:131]
	ds_read_b128 v[186:189], v248
	v_mfma_f32_16x16x32_bf16 v[68:71], v[16:19], v[4:7], v[68:71]
	ds_read_b128 v[212:215], v249 offset:8192
	v_mfma_f32_16x16x32_bf16 v[108:111], v[16:19], v[8:11], v[108:111]
	ds_read_b128 v[190:193], v248 offset:1024
	v_mfma_f32_16x16x32_bf16 v[132:135], v[16:19], v[12:15], v[132:135]
	ds_read_b128 v[216:219], v249 offset:9216
	v_mfma_f32_16x16x32_bf16 v[120:123], v[20:23], v[0:3], v[120:123]
	ds_read_b128 v[194:197], v248 offset:2048
	v_mfma_f32_16x16x32_bf16 v[64:67], v[20:23], v[4:7], v[64:67]
	ds_read_b128 v[220:223], v249 offset:10240
	v_mfma_f32_16x16x32_bf16 v[112:115], v[20:23], v[8:11], v[112:115]
	ds_read_b128 v[208:211], v248 offset:3072
	v_mfma_f32_16x16x32_bf16 v[136:139], v[20:23], v[12:15], v[136:139]
	ds_read_b128 v[224:227], v249 offset:11264
	v_mfma_f32_16x16x32_bf16 v[104:107], v[162:165], v[0:3], v[104:107]
	ds_read_b128 v[228:231], v249 offset:12288
	v_mfma_f32_16x16x32_bf16 v[56:59], v[162:165], v[4:7], v[56:59]
	ds_read_b128 v[232:235], v249 offset:13312
	v_mfma_f32_16x16x32_bf16 v[116:119], v[162:165], v[8:11], v[116:119]
	ds_read_b128 v[236:239], v249 offset:14336
	v_mfma_f32_16x16x32_bf16 v[140:143], v[162:165], v[12:15], v[140:143]
	ds_read_b128 v[240:243], v249 offset:15360
	s_add_u32 m0, s25, s24
	v_mfma_f32_16x16x32_bf16 v[100:103], v[166:169], v[0:3], v[100:103]
	global_load_lds_dwordx4 v244, s[26:27]
	v_mfma_f32_16x16x32_bf16 v[52:55], v[166:169], v[4:7], v[52:55]
	v_mfma_f32_16x16x32_bf16 v[124:127], v[166:169], v[8:11], v[124:127]
	s_add_u32 m0, m0, 0x1000
	v_mfma_f32_16x16x32_bf16 v[144:147], v[166:169], v[12:15], v[144:147]
	global_load_lds_dwordx4 v245, s[26:27]
	v_mfma_f32_16x16x32_bf16 v[60:63], v[170:173], v[0:3], v[60:63]
	v_mfma_f32_16x16x32_bf16 v[36:39], v[170:173], v[4:7], v[36:39]
	s_add_u32 m0, m0, 0x1000
	v_mfma_f32_16x16x32_bf16 v[80:83], v[170:173], v[8:11], v[80:83]
	global_load_lds_dwordx4 v244, s[28:29]
	v_mfma_f32_16x16x32_bf16 v[96:99], v[170:173], v[12:15], v[96:99]
	v_mfma_f32_16x16x32_bf16 v[48:51], v[174:177], v[0:3], v[48:51]
	s_add_u32 m0, m0, 0x1000
	v_mfma_f32_16x16x32_bf16 v[32:35], v[174:177], v[4:7], v[32:35]
	global_load_lds_dwordx4 v245, s[28:29]
	v_mfma_f32_16x16x32_bf16 v[88:91], v[174:177], v[8:11], v[88:91]
	v_mfma_f32_16x16x32_bf16 v[84:87], v[174:177], v[12:15], v[84:87]
	s_add_u32 m0, m0, 0x1000
	v_mfma_f32_16x16x32_bf16 v[44:47], v[178:181], v[0:3], v[44:47]
	global_load_lds_dwordx4 v246, s[28:29]
	v_mfma_f32_16x16x32_bf16 v[28:31], v[178:181], v[4:7], v[28:31]
	v_mfma_f32_16x16x32_bf16 v[92:95], v[178:181], v[8:11], v[92:95]
	s_add_u32 m0, m0, 0x1000
	v_mfma_f32_16x16x32_bf16 v[72:75], v[178:181], v[12:15], v[72:75]
	global_load_lds_dwordx4 v247, s[28:29]
	v_mfma_f32_16x16x32_bf16 v[40:43], v[182:185], v[0:3], v[40:43]
	v_mfma_f32_16x16x32_bf16 v[24:27], v[182:185], v[4:7], v[24:27]
	v_mfma_f32_16x16x32_bf16 v[76:79], v[182:185], v[8:11], v[76:79]
	v_mfma_f32_16x16x32_bf16 v[148:151], v[182:185], v[12:15], v[148:151]
	s_add_u32 s26, s26, 64
	s_addc_u32 s27, s27, 0
	s_add_u32 s28, s28, 64
	s_addc_u32 s29, s29, 0
	s_add_u32 s25, s25, 24576
	s_cmp_eq_u32 s25, 73728
	s_cselect_b32 s25, 0, s25
	s_add_u32 s30, s30, 24576
	s_cmp_eq_u32 s30, 73728
	s_cselect_b32 s30, 0, s30
	s_waitcnt vmcnt(6)
	s_waitcnt lgkmcnt(0)
	s_barrier
	s_sub_u32 s31, s31, 1
	s_cmp_lg_u32 s31, 0
	s_cbranch_scc1 .Lgm3_loop
	v_add_u32_e32 v248, s30, v155
	v_add_u32_e32 v249, s30, v160
	v_mfma_f32_16x16x32_bf16 v[128:131], v[212:215], v[186:189], v[128:131]
	ds_read_b128 v[0:3], v248
	v_mfma_f32_16x16x32_bf16 v[68:71], v[212:215], v[190:193], v[68:71]
	ds_read_b128 v[16:19], v249 offset:8192
	v_mfma_f32_16x16x32_bf16 v[108:111], v[212:215], v[194:197], v[108:111]
	ds_read_b128 v[4:7], v248 offset:1024
	v_mfma_f32_16x16x32_bf16 v[132:135], v[212:215], v[208:211], v[132:135]
	ds_read_b128 v[20:23], v249 offset:9216
	v_mfma_f32_16x16x32_bf16 v[120:123], v[216:219], v[186:189], v[120:123]
	ds_read_b128 v[8:11], v248 offset:2048
	v_mfma_f32_16x16x32_bf16 v[64:67], v[216:219], v[190:193], v[64:67]
	ds_read_b128 v[162:165], v249 offset:10240
	v_mfma_f32_16x16x32_bf16 v[112:115], v[216:219], v[194:197], v[112:115]
	ds_read_b128 v[12:15], v248 offset:3072
	v_mfma_f32_16x16x32_bf16 v[136:139], v[216:219], v[208:211], v[136:139]
	ds_read_b128 v[166:169], v249 offset:11264
	v_mfma_f32_16x16x32_bf16 v[104:107], v[220:223], v[186:189], v[104:107]
	ds_read_b128 v[170:173], v249 offset:12288
	v_mfma_f32_16x16x32_bf16 v[56:59], v[220:223], v[190:193], v[56:59]
	ds_read_b128 v[174:177], v249 offset:13312
	v_mfma_f32_16x16x32_bf16 v[116:119], v[220:223], v[194:197], v[116:119]
	ds_read_b128 v[178:181], v249 offset:14336
	v_mfma_f32_16x16x32_bf16 v[140:143], v[220:223], v[208:211], v[140:143]
	ds_read_b128 v[182:185], v249 offset:15360
	s_add_u32 m0, s25, s24
	v_mfma_f32_16x16x32_bf16 v[100:103], v[224:227], v[186:189], v[100:103]
	global_load_lds_dwordx4 v244, s[26:27]
	v_mfma_f32_16x16x32_bf16 v[52:55], v[224:227], v[190:193], v[52:55]
	v_mfma_f32_16x16x32_bf16 v[124:127], v[224:227], v[194:197], v[124:127]
	s_add_u32 m0, m0, 0x1000
	v_mfma_f32_16x16x32_bf16 v[144:147], v[224:227], v[208:211], v[144:147]
	global_load_lds_dwordx4 v245, s[26:27]
	v_mfma_f32_16x16x32_bf16 v[60:63], v[228:231], v[186:189], v[60:63]
	v_mfma_f32_16x16x32_bf16 v[36:39], v[228:231], v[190:193], v[36:39]
	s_add_u32 m0, m0, 0x1000
	v_mfma_f32_16x16x32_bf16 v[80:83], v[228:231], v[194:197], v[80:83]
	global_load_lds_dwordx4 v244, s[28:29]
	v_mfma_f32_16x16x32_bf16 v[96:99], v[228:231], v[208:211], v[96:99]
	v_mfma_f32_16x16x32_bf16 v[48:51], v[232:235], v[186:189], v[48:51]
	s_add_u32 m0, m0, 0x1000
	v_mfma_f32_16x16x32_bf16 v[32:35], v[232:235], v[190:193], v[32:35]
	global_load_lds_dwordx4 v245, s[28:29]
	v_mfma_f32_16x16x32_bf16 v[88:91], v[232:235], v[194:197], v[88:91]
	v_mfma_f32_16x16x32_bf16 v[84:87], v[232:235], v[208:211], v[84:87]
	s_add_u32 m0, m0, 0x1000
	v_mfma_f32_16x16x32_bf16 v[44:47], v[236:239], v[186:189], v[44:47]
	global_load_lds_dwordx4 v246, s[28:29]
	v_mfma_f32_16x16x32_bf16 v[28:31], v[236:239], v[190:193], v[28:31]
	v_mfma_f32_16x16x32_bf16 v[92:95], v[236:239], v[194:197], v[92:95]
	s_add_u32 m0, m0, 0x1000
	v_mfma_f32_16x16x32_bf16 v[72:75], v[236:239], v[208:211], v[72:75]
	global_load_lds_dwordx4 v247, s[28:29]
	v_mfma_f32_16x16x32_bf16 v[40:43], v[240:243], v[186:189], v[40:43]
	v_mfma_f32_16x16x32_bf16 v[24:27], v[240:243], v[190:193], v[24:27]
	v_mfma_f32_16x16x32_bf16 v[76:79], v[240:243], v[194:197], v[76:79]
	v_mfma_f32_16x16x32_bf16 v[148:151], v[240:243], v[208:211], v[148:151]
	s_add_u32 s26, s26, 64
	s_addc_u32 s27, s27, 0
	s_add_u32 s28, s28, 64
	s_addc_u32 s29, s29, 0
	s_add_u32 s25, s25, 24576
	s_cmp_eq_u32 s25, 73728
	s_cselect_b32 s25, 0, s25
	s_add_u32 s30, s30, 24576
	s_cmp_eq_u32 s30, 73728
	s_cselect_b32 s30, 0, s30
	s_waitcnt vmcnt(6)
	s_waitcnt lgkmcnt(0)
	s_barrier
	v_mfma_f32_16x16x32_bf16 v[128:131], v[16:19], v[0:3], v[128:131]
	v_mfma_f32_16x16x32_bf16 v[68:71], v[16:19], v[4:7], v[68:71]
	v_mfma_f32_16x16x32_bf16 v[108:111], v[16:19], v[8:11], v[108:111]
	v_mfma_f32_16x16x32_bf16 v[132:135], v[16:19], v[12:15], v[132:135]
	v_mfma_f32_16x16x32_bf16 v[120:123], v[20:23], v[0:3], v[120:123]
	v_mfma_f32_16x16x32_bf16 v[64:67], v[20:23], v[4:7], v[64:67]
	v_mfma_f32_16x16x32_bf16 v[112:115], v[20:23], v[8:11], v[112:115]
	v_mfma_f32_16x16x32_bf16 v[136:139], v[20:23], v[12:15], v[136:139]
	v_mfma_f32_16x16x32_bf16 v[104:107], v[162:165], v[0:3], v[104:107]
	v_mfma_f32_16x16x32_bf16 v[56:59], v[162:165], v[4:7], v[56:59]
	v_mfma_f32_16x16x32_bf16 v[116:119], v[162:165], v[8:11], v[116:119]
	v_mfma_f32_16x16x32_bf16 v[140:143], v[162:165], v[12:15], v[140:143]
	v_mfma_f32_16x16x32_bf16 v[100:103], v[166:169], v[0:3], v[100:103]
	v_mfma_f32_16x16x32_bf16 v[52:55], v[166:169], v[4:7], v[52:55]
	v_mfma_f32_16x16x32_bf16 v[124:127], v[166:169], v[8:11], v[124:127]
	v_mfma_f32_16x16x32_bf16 v[144:147], v[166:169], v[12:15], v[144:147]
	v_mfma_f32_16x16x32_bf16 v[60:63], v[170:173], v[0:3], v[60:63]
	v_mfma_f32_16x16x32_bf16 v[36:39], v[170:173], v[4:7], v[36:39]
	v_mfma_f32_16x16x32_bf16 v[80:83], v[170:173], v[8:11], v[80:83]
	v_mfma_f32_16x16x32_bf16 v[96:99], v[170:173], v[12:15], v[96:99]
	v_mfma_f32_16x16x32_bf16 v[48:51], v[174:177], v[0:3], v[48:51]
	v_mfma_f32_16x16x32_bf16 v[32:35], v[174:177], v[4:7], v[32:35]
	v_mfma_f32_16x16x32_bf16 v[88:91], v[174:177], v[8:11], v[88:91]
	v_mfma_f32_16x16x32_bf16 v[84:87], v[174:177], v[12:15], v[84:87]
	v_mfma_f32_16x16x32_bf16 v[44:47], v[178:181], v[0:3], v[44:47]
	v_mfma_f32_16x16x32_bf16 v[28:31], v[178:181], v[4:7], v[28:31]
	v_mfma_f32_16x16x32_bf16 v[92:95], v[178:181], v[8:11], v[92:95]
	v_mfma_f32_16x16x32_bf16 v[72:75], v[178:181], v[12:15], v[72:75]
	v_mfma_f32_16x16x32_bf16 v[40:43], v[182:185], v[0:3], v[40:43]
	v_mfma_f32_16x16x32_bf16 v[24:27], v[182:185], v[4:7], v[24:27]
	v_mfma_f32_16x16x32_bf16 v[76:79], v[182:185], v[8:11], v[76:79]
	v_mfma_f32_16x16x32_bf16 v[148:151], v[182:185], v[12:15], v[148:151]
	s_waitcnt vmcnt(0)
	s_waitcnt lgkmcnt(0)
	s_barrier
	s_branch .Lgm3_tail
.Lgm3_cheap:
	v_add_u32_e32 v248, s30, v155
	v_add_u32_e32 v249, s30, v160
	v_mfma_f32_16x16x32_bf16 v[128:131], v[212:215], v[186:189], v[128:131]
	ds_read_b128 v[0:3], v248
	v_mfma_f32_16x16x32_bf16 v[68:71], v[212:215], v[190:193], v[68:71]
	ds_read_b128 v[16:19], v249 offset:8192
	v_mfma_f32_16x16x32_bf16 v[108:111], v[212:215], v[194:197], v[108:111]
	ds_read_b128 v[4:7], v248 offset:1024
	v_mfma_f32_16x16x32_bf16 v[132:135], v[212:215], v[208:211], v[132:135]
	ds_read_b128 v[20:23], v249 offset:9216
	v_mfma_f32_16x16x32_bf16 v[120:123], v[216:219], v[186:189], v[120:123]
	ds_read_b128 v[8:11], v248 offset:2048
	s_add_u32 m0, s25, s24
	v_mfma_f32_16x16x32_bf16 v[64:67], v[216:219], v[190:193], v[64:67]
	ds_read_b128 v[12:15], v248 offset:3072
	global_load_lds_dwordx4 v244, s[26:27]
	s_add_u32 m0, m0, 0x1000
	v_mfma_f32_16x16x32_bf16 v[112:115], v[216:219], v[194:197], v[112:115]
	global_load_lds_dwordx4 v245, s[26:27]
	s_add_u32 m0, m0, 0x1000
	v_mfma_f32_16x16x32_bf16 v[136:139], v[216:219], v[208:211], v[136:139]
	global_load_lds_dwordx4 v244, s[28:29]
	s_add_u32 s26, s26, 64
	s_addc_u32 s27, s27, 0
	s_add_u32 s28, s28, 64
	s_addc_u32 s29, s29, 0
	s_add_u32 s25, s25, 24576
	s_cmp_eq_u32 s25, 73728
	s_cselect_b32 s25, 0, s25
	s_add_u32 s30, s30, 24576
	s_cmp_eq_u32 s30, 73728
	s_cselect_b32 s30, 0, s30
	s_waitcnt vmcnt(3)
	s_waitcnt lgkmcnt(0)
	s_barrier
	v_add_u32_e32 v248, s30, v155
	v_add_u32_e32 v249, s30, v160
	v_mfma_f32_16x16x32_bf16 v[128:131], v[16:19], v[0:3], v[128:131]
	ds_read_b128 v[186:189], v248
	v_mfma_f32_16x16x32_bf16 v[68:71], v[16:19], v[4:7], v[68:71]
	ds_read_b128 v[212:215], v249 offset:8192
	v_mfma_f32_16x16x32_bf16 v[108:111], v[16:19], v[8:11], v[108:111]
	ds_read_b128 v[190:193], v248 offset:1024
	v_mfma_f32_16x16x32_bf16 v[132:135], v[16:19], v[12:15], v[132:135]
	ds_read_b128 v[216:219], v249 offset:9216
	v_mfma_f32_16x16x32_bf16 v[120:123], v[20:23], v[0:3], v[120:123]
	ds_read_b128 v[194:197], v248 offset:2048
	s_add_u32 m0, s25, s24
	v_mfma_f32_16x16x32_bf16 v[64:67], v[20:23], v[4:7], v[64:67]
	ds_read_b128 v[208:211], v248 offset:3072
	global_load_lds_dwordx4 v244, s[26:27]
	s_add_u32 m0, m0, 0x1000
	v_mfma_f32_16x16x32_bf16 v[112:115], v[20:23], v[8:11], v[112:115]
	global_load_lds_dwordx4 v245, s[26:27]
	s_add_u32 m0, m0, 0x1000
	v_mfma_f32_16x16x32_bf16 v[136:139], v[20:23], v[12:15], v[136:139]
	global_load_lds_dwordx4 v244, s[28:29]
	s_add_u32 s26, s26, 64
	s_addc_u32 s27, s27, 0
	s_add_u32 s28, s28, 64
	s_addc_u32 s29, s29, 0
	s_add_u32 s25, s25, 24576
	s_cmp_eq_u32 s25, 73728
	s_cselect_b32 s25, 0, s25
	s_add_u32 s30, s30, 24576
	s_cmp_eq_u32 s30, 73728
	s_cselect_b32 s30, 0, s30
	s_waitcnt vmcnt(3)
	s_waitcnt lgkmcnt(0)
	s_barrier
	s_sub_u32 s31, s31, 1
	s_cmp_lg_u32 s31, 0
	s_cbranch_scc1 .Lgm3_cheap
	v_add_u32_e32 v248, s30, v155
	v_add_u32_e32 v249, s30, v160
	v_mfma_f32_16x16x32_bf16 v[128:131], v[212:215], v[186:189], v[128:131]
	ds_read_b128 v[0:3], v248
	v_mfma_f32_16x16x32_bf16 v[68:71], v[212:215], v[190:193], v[68:71]
	ds_read_b128 v[16:19], v249 offset:8192
	v_mfma_f32_16x16x32_bf16 v[108:111], v[212:215], v[194:197], v[108:111]
	ds_read_b128 v[4:7], v248 offset:1024
	v_mfma_f32_16x16x32_bf16 v[132:135], v[212:215], v[208:211], v[132:135]
	ds_read_b128 v[20:23], v249 offset:9216
	v_mfma_f32_16x16x32_bf16 v[120:123], v[216:219], v[186:189], v[120:123]
	ds_read_b128 v[8:11], v248 offset:2048
	s_add_u32 m0, s25, s24
	v_mfma_f32_16x16x32_bf16 v[64:67], v[216:219], v[190:193], v[64:67]
	ds_read_b128 v[12:15], v248 offset:3072
	global_load_lds_dwordx4 v244, s[26:27]
	s_add_u32 m0, m0, 0x1000
	v_mfma_f32_16x16x32_bf16 v[112:115], v[216:219], v[194:197], v[112:115]
	global_load_lds_dwordx4 v245, s[26:27]
	s_add_u32 m0, m0, 0x1000
	v_mfma_f32_16x16x32_bf16 v[136:139], v[216:219], v[208:211], v[136:139]
	global_load_lds_dwordx4 v244, s[28:29]
	s_add_u32 s26, s26, 64
	s_addc_u32 s27, s27, 0
	s_add_u32 s28, s28, 64
	s_addc_u32 s29, s29, 0
	s_add_u32 s25, s25, 24576
	s_cmp_eq_u32 s25, 73728
	s_cselect_b32 s25, 0, s25
	s_add_u32 s30, s30, 24576
	s_cmp_eq_u32 s30, 73728
	s_cselect_b32 s30, 0, s30
	s_waitcnt vmcnt(3)
	s_waitcnt lgkmcnt(0)
	s_barrier
	v_mfma_f32_16x16x32_bf16 v[128:131], v[16:19], v[0:3], v[128:131]
	v_mfma_f32_16x16x32_bf16 v[68:71], v[16:19], v[4:7], v[68:71]
	v_mfma_f32_16x16x32_bf16 v[108:111], v[16:19], v[8:11], v[108:111]
	v_mfma_f32_16x16x32_bf16 v[132:135], v[16:19], v[12:15], v[132:135]
	v_mfma_f32_16x16x32_bf16 v[120:123], v[20:23], v[0:3], v[120:123]
	v_mfma_f32_16x16x32_bf16 v[64:67], v[20:23], v[4:7], v[64:67]
	v_mfma_f32_16x16x32_bf16 v[112:115], v[20:23], v[8:11], v[112:115]
	v_mfma_f32_16x16x32_bf16 v[136:139], v[20:23], v[12:15], v[136:139]
	s_waitcnt vmcnt(0)
	s_waitcnt lgkmcnt(0)
	s_barrier
.Lgm3_tail:
	ds_read_b128 v[156:159], v160 offset:8192
	ds_read_b128 v[162:165], v160 offset:9216
	ds_read_b128 v[166:169], v155
	ds_read_b128 v[170:173], v155 offset:1024
	ds_read_b128 v[174:177], v160 offset:10240
	s_waitcnt lgkmcnt(2)
	v_mfma_f32_16x16x32_bf16 v[178:181], v[162:165], v[166:169], v[120:123]
	s_nop 2
	ds_read_b128 v[120:123], v160 offset:11264
	ds_read_b128 v[182:185], v155 offset:2048
	ds_read_b128 v[186:189], v155 offset:3072
	s_waitcnt lgkmcnt(1)
	v_mfma_f32_16x16x32_bf16 v[190:193], v[156:159], v[182:185], v[108:111]
	s_nop 2
	ds_read_b128 v[108:111], v160 offset:12288
	v_mfma_f32_16x16x32_bf16 v[100:103], v[120:123], v[166:169], v[100:103]
	v_mfma_f32_16x16x32_bf16 v[52:55], v[120:123], v[170:173], v[52:55]
	v_mfma_f32_16x16x32_bf16 v[194:197], v[162:165], v[182:185], v[112:115]
	v_mfma_f32_16x16x32_bf16 v[208:211], v[174:177], v[182:185], v[116:119]
	s_nop 1
	ds_read_b128 v[112:115], v160 offset:13312
	v_mfma_f32_16x16x32_bf16 v[212:215], v[120:123], v[182:185], v[124:127]
	ds_read_b128 v[116:119], v160 offset:14336
	s_waitcnt lgkmcnt(3)
	v_mfma_f32_16x16x32_bf16 v[144:147], v[120:123], v[186:189], v[144:147]
	ds_read_b128 v[120:123], v160 offset:15360
	s_waitcnt vmcnt(4)
	s_waitcnt vmcnt(3)
	s_waitcnt vmcnt(2)
	s_waitcnt vmcnt(1)
	s_waitcnt vmcnt(0)
	s_waitcnt lgkmcnt(0)
	s_barrier
	ds_read_b128 v[0:3], v160 offset:32768
	v_mfma_f32_16x16x32_bf16 v[128:131], v[156:159], v[166:169], v[128:131]
	ds_read_b128 v[4:7], v160 offset:33792
	ds_read_b128 v[8:11], v155 offset:24576
	ds_read_b128 v[16:19], v155 offset:25600
	ds_read_b128 v[20:23], v160 offset:34816
	v_mfma_f32_16x16x32_bf16 v[68:71], v[156:159], v[170:173], v[68:71]
	v_mfma_f32_16x16x32_bf16 v[64:67], v[162:165], v[170:173], v[64:67]
	v_mfma_f32_16x16x32_bf16 v[56:59], v[174:177], v[170:173], v[56:59]
	v_mfma_f32_16x16x32_bf16 v[40:43], v[120:123], v[166:169], v[40:43]
	v_mfma_f32_16x16x32_bf16 v[36:39], v[108:111], v[170:173], v[36:39]
	v_mfma_f32_16x16x32_bf16 v[32:35], v[112:115], v[170:173], v[32:35]
	v_mfma_f32_16x16x32_bf16 v[28:31], v[116:119], v[170:173], v[28:31]
	v_mfma_f32_16x16x32_bf16 v[24:27], v[120:123], v[170:173], v[24:27]
	v_mfma_f32_16x16x32_bf16 v[170:173], v[120:123], v[182:185], v[76:79]
	v_mfma_f32_16x16x32_bf16 v[12:15], v[120:123], v[186:189], v[148:151]
	s_waitcnt lgkmcnt(2)
	v_mfma_f32_16x16x32_bf16 v[120:123], v[0:3], v[8:11], v[128:131]
	s_nop 2
	ds_read_b128 v[128:131], v160 offset:35840
	v_mfma_f32_16x16x32_bf16 v[124:127], v[4:7], v[8:11], v[178:181]
	ds_read_b128 v[148:151], v155 offset:26624
	s_nop 1
	ds_read_b128 v[178:181], v155 offset:27648
	v_mfma_f32_16x16x32_bf16 v[104:107], v[174:177], v[166:169], v[104:107]
	v_mfma_f32_16x16x32_bf16 v[132:135], v[156:159], v[186:189], v[132:135]
	v_mfma_f32_16x16x32_bf16 v[136:139], v[162:165], v[186:189], v[136:139]
	v_mfma_f32_16x16x32_bf16 v[140:143], v[174:177], v[186:189], v[140:143]
	v_mfma_f32_16x16x32_bf16 v[60:63], v[108:111], v[166:169], v[60:63]
	v_mfma_f32_16x16x32_bf16 v[48:51], v[112:115], v[166:169], v[48:51]
	v_mfma_f32_16x16x32_bf16 v[44:47], v[116:119], v[166:169], v[44:47]
	v_mfma_f32_16x16x32_bf16 v[156:159], v[108:111], v[182:185], v[80:83]
	v_mfma_f32_16x16x32_bf16 v[162:165], v[112:115], v[182:185], v[88:91]
	v_mfma_f32_16x16x32_bf16 v[166:169], v[116:119], v[182:185], v[92:95]
	v_mfma_f32_16x16x32_bf16 v[174:177], v[108:111], v[186:189], v[96:99]
	v_mfma_f32_16x16x32_bf16 v[182:185], v[112:115], v[186:189], v[84:87]
	v_mfma_f32_16x16x32_bf16 v[216:219], v[116:119], v[186:189], v[72:75]
	s_waitcnt lgkmcnt(3)
	v_mfma_f32_16x16x32_bf16 v[116:119], v[20:23], v[8:11], v[104:107]
	s_waitcnt lgkmcnt(2)
	v_mfma_f32_16x16x32_bf16 v[112:115], v[128:131], v[8:11], v[100:103]
	v_mfma_f32_16x16x32_bf16 v[108:111], v[0:3], v[16:19], v[68:71]
	v_mfma_f32_16x16x32_bf16 v[104:107], v[4:7], v[16:19], v[64:67]
	v_mfma_f32_16x16x32_bf16 v[96:99], v[128:131], v[16:19], v[52:55]
	s_waitcnt lgkmcnt(1)
	v_mfma_f32_16x16x32_bf16 v[92:95], v[0:3], v[148:151], v[190:193]
	v_mfma_f32_16x16x32_bf16 v[88:91], v[4:7], v[148:151], v[194:197]
	v_mfma_f32_16x16x32_bf16 v[80:83], v[128:131], v[148:151], v[212:215]
	s_waitcnt lgkmcnt(0)
	v_mfma_f32_16x16x32_bf16 v[76:79], v[0:3], v[178:181], v[132:135]
	ds_read_b128 v[0:3], v160 offset:36864
	v_mfma_f32_16x16x32_bf16 v[72:75], v[4:7], v[178:181], v[136:139]
	ds_read_b128 v[4:7], v160 offset:37888
	v_mfma_f32_16x16x32_bf16 v[68:71], v[128:131], v[178:181], v[144:147]
	ds_read_b128 v[130:133], v160 offset:38912
	ds_read_b128 v[134:137], v160 offset:39936
	s_waitcnt lgkmcnt(0)
	v_mfma_f32_16x16x32_bf16 v[100:103], v[20:23], v[16:19], v[56:59]
	s_barrier
	v_mov_b32 v128, v198
	v_mfma_f32_16x16x32_bf16 v[52:55], v[0:3], v[8:11], v[60:63]
	v_and_b32_e32 v129, 63, v128
	v_mfma_f32_16x16x32_bf16 v[56:59], v[4:7], v[8:11], v[48:51]
	v_mfma_f32_16x16x32_bf16 v[60:63], v[130:133], v[8:11], v[44:47]
	v_mfma_f32_16x16x32_bf16 v[48:51], v[134:137], v[8:11], v[40:43]
	v_lshrrev_b32_e32 v8, 1, v128
	v_mfma_f32_16x16x32_bf16 v[84:87], v[20:23], v[148:151], v[208:211]
	v_mfma_f32_16x16x32_bf16 v[64:67], v[20:23], v[178:181], v[140:143]
	v_mfma_f32_16x16x32_bf16 v[44:47], v[0:3], v[16:19], v[36:39]
	v_mfma_f32_16x16x32_bf16 v[40:43], v[4:7], v[16:19], v[32:35]
	v_mfma_f32_16x16x32_bf16 v[36:39], v[130:133], v[16:19], v[28:31]
	v_mfma_f32_16x16x32_bf16 v[32:35], v[134:137], v[16:19], v[24:27]
	v_mfma_f32_16x16x32_bf16 v[28:31], v[0:3], v[148:151], v[156:159]
	v_mfma_f32_16x16x32_bf16 v[20:23], v[4:7], v[148:151], v[162:165]
	v_mfma_f32_16x16x32_bf16 v[16:19], v[130:133], v[148:151], v[166:169]
	v_mfma_f32_16x16x32_bf16 v[24:27], v[134:137], v[148:151], v[170:173]
	v_and_or_b32 v148, v8, 64, s4
	v_lshlrev_b32_e32 v8, 1, v128
	v_and_b32_e32 v8, 0x80, v8
	v_mfma_f32_16x16x32_bf16 v[0:3], v[0:3], v[178:181], v[174:177]
	v_or_b32_e32 v151, s17, v8
	v_lshrrev_b32_e32 v150, 6, v151
	s_movk_i32 s4, 0xc01
	v_mfma_f32_16x16x32_bf16 v[4:7], v[4:7], v[178:181], v[182:185]
	v_and_b32_e32 v149, 15, v128
	v_cmp_gt_u32_e32 vcc, s4, v151
	v_and_b32_e32 v156, 60, v150
	v_mfma_f32_16x16x32_bf16 v[8:11], v[130:133], v[178:181], v[216:219]
	v_mfma_f32_16x16x32_bf16 v[12:15], v[134:137], v[178:181], v[12:15]
	s_and_saveexec_b64 s[20:21], vcc
	s_cbranch_execz .LBB0_591
	v_cmp_ne_u32_e32 vcc, 8, v156
	s_and_saveexec_b64 s[6:7], vcc
	s_xor_b64 s[6:7], exec, s[6:7]
	s_cbranch_execz .LBB0_485
	s_and_b32 s4, s17, 0xe00
	s_cmpk_eq_i32 s4, 0x400
	s_cbranch_scc1 .LBB0_616
	v_cmp_lt_i32_e32 vcc, 31, v150
	s_mov_b64 s[34:35], 0
	s_mov_b64 s[28:29], 0
	s_and_saveexec_b64 s[4:5], vcc
	s_xor_b64 s[4:5], exec, s[4:5]
	s_cbranch_execz .LBB0_462
	v_cmp_lt_i32_e32 vcc, 33, v150
	s_mov_b64 s[22:23], 0
	s_mov_b64 s[24:25], 0
	s_and_saveexec_b64 s[26:27], vcc
	s_xor_b64 s[26:27], exec, s[26:27]
	s_cbranch_execz .LBB0_459
	v_cmp_eq_u32_e32 vcc, 34, v150
	s_mov_b64 s[24:25], -1
	s_and_saveexec_b64 s[28:29], vcc
	s_xor_b64 s[24:25], exec, -1
	s_or_b64 exec, exec, s[28:29]
	s_and_b64 s[24:25], s[24:25], exec
